# v3 + ret_out final stage rewritten (4 rows per wave pass, 8 cols per lane) + ret_out staging loads batched 9+7
# speedup vs baseline: 1.0093x; 1.0093x over previous
; #define LAS __attribute__((address_space(3)))
; __device__ __forceinline__ float head_l2g(int h) { return __log2f(1.0f - exp2f(-5.0f - (float)h)); }
; __device__ __forceinline__ void ret_out_unit(LAS unsigned char* lds, const bf16* Z, const bf16* RT, const float* subg, bf16* YB, int h, int n, int tid) {
;     ...
;     const float l2g = head_l2g(h);
;     const bf16* zb = Z + (size_t)(n * 128) * NIN + h * 128;
;     const bf16* rt = RT + (size_t)(h * 128 + n) * 16384;
; #pragma unroll
;     for (int i = 0; i < 4; ++i) {
;         const int pc = tid + 512 * i, t = pc >> 4, c8 = pc & 15;
;         const v4u q = *(const v4u*)(zb + (size_t)t * NIN + ZQR + c8 * 8);
;         const v4u k = *(const v4u*)(zb + (size_t)t * NIN + ZKR + c8 * 8);
;         const v4u r = *(const v4u*)(rt + t * 128 + c8 * 8);
;         *(LAS v4u*)(Qs + t * TP + c8 * 16) = q; *(LAS v4u*)(Ks + t * TP + c8 * 16) = k; *(LAS v4u*)(Rs + t * TP + c8 * 16) = r;
;     }
; #pragma unroll
;     for (int i = 0; i < 4; ++i) {
;         const int kq = i * 8 + wid, c8 = kq >> 1, t = (kq & 1) * 64 + lane;
;         const v4u v = *(const v4u*)(zb + (size_t)t * NIN + ZVR + c8 * 8);
;         lds_scatter8(VT, c8 * 8, t, v);
;     }
;     __syncthreads();
.LBB0_14:
	s_and_b32 s1, s3, 0x7f
	s_nop 0
	v_lshl_add_u32 v2, s1, 7, v143
	s_ashr_i32 s1, s0, 7
	v_cvt_f32_i32_e32 v0, s1
	s_and_b32 s70, s0, 0xffffff80
	s_ashr_i32 s71, s70, 31
	s_lshl_b64 s[78:79], s[70:71], 1
	v_ashrrev_i32_e32 v3, 31, v2
	v_mad_i64_i32 v[92:93], s[70:71], v2, s33, v[88:89]
	v_sub_f32_e32 v0, 0xc0a00000, v0
	v_lshlrev_b64 v[2:3], 11, v[2:3]
	v_cmp_gt_f32_e64 s[70:71], s96, v0
	v_lshl_add_u64 v[94:95], v[88:89], 0, v[2:3]
	s_and_b32 s69, s0, 0x7f
	v_cndmask_b32_e64 v2, 0, v234, s[70:71]
	v_add_f32_e32 v0, v0, v2
	v_exp_f32_e32 v0, v0
	s_and_b64 s[70:71], s[70:71], exec
	s_cselect_b32 s1, 0xffffffc0, 0
	s_mul_i32 s69, s69, 0x2c0000
	v_readlane_b32 s70, v254, 35
	v_ldexp_f32 v0, v0, s1
	v_readlane_b32 s71, v254, 36
	s_add_u32 s1, s70, s69
	s_addc_u32 s69, s71, 0
	s_add_u32 s76, s1, s78
	s_addc_u32 s77, s69, s79
	s_ashr_i32 s1, s0, 31
	v_lshl_add_u64 v[2:3], s[76:77], 0, v[68:69]
	s_lshl_b64 s[70:71], s[0:1], 15
	v_lshl_add_u64 v[6:7], v[2:3], 0, v[192:193]
	s_movk_i32 s1, 0x1000
	v_lshl_add_u64 v[14:15], v[66:67], 0, s[70:71]
	v_add_co_u32_e64 v2, s[70:71], s1, v6
	v_lshl_add_u64 v[10:11], v[70:71], 1, v[14:15]
	s_nop 0
	v_addc_co_u32_e64 v3, s[70:71], 0, v7, s[70:71]
	v_add_co_u32_e64 v6, s[70:71], s93, v6
	global_load_dwordx4 v[208:211], v[2:3], off offset:2048
	s_nop 0
	v_addc_co_u32_e64 v7, s[70:71], 0, v7, s[70:71]
	global_load_dwordx4 v[212:215], v[6:7], off
	global_load_dwordx4 v[216:219], v[10:11], off
	v_mov_b32_e32 v91, v193
	v_sub_f32_e32 v0, 1.0, v0
	v_log_f32_e32 v0, v0
	s_mov_b32 s5, 0
	v_lshl_add_u64 v[2:3], s[76:77], 0, v[72:73]
	v_lshl_add_u64 v[6:7], v[2:3], 0, v[192:193]
	v_add_co_u32_e64 v2, s[70:71], s1, v6
	v_lshl_add_u64 v[10:11], v[74:75], 1, v[14:15]
	s_nop 0
	v_addc_co_u32_e64 v3, s[70:71], 0, v7, s[70:71]
	v_add_co_u32_e64 v6, s[70:71], s93, v6
	global_load_dwordx4 v[220:223], v[2:3], off offset:2048
	s_nop 0
	v_addc_co_u32_e64 v7, s[70:71], 0, v7, s[70:71]
	global_load_dwordx4 v[226:229], v[6:7], off
	s_nop 0
	global_load_dwordx4 v[238:241], v[10:11], off
	v_lshl_add_u64 v[2:3], s[76:77], 0, v[76:77]
	v_lshl_add_u64 v[6:7], v[2:3], 0, v[192:193]
	v_add_co_u32_e64 v2, s[70:71], s1, v6
	v_lshl_add_u64 v[10:11], v[78:79], 1, v[14:15]
	s_nop 0
	v_addc_co_u32_e64 v3, s[70:71], 0, v7, s[70:71]
	v_add_co_u32_e64 v6, s[70:71], s93, v6
	global_load_dwordx4 v[242:245], v[2:3], off offset:2048
	s_nop 0
	v_addc_co_u32_e64 v7, s[70:71], 0, v7, s[70:71]
	global_load_dwordx4 v[246:249], v[6:7], off
	s_nop 0
	global_load_dwordx4 v[250:253], v[10:11], off
	s_waitcnt vmcnt(0)
	v_add_u32_e32 v194, v96, v98
	v_add_u32_e32 v195, v97, v98
	ds_write_b128 v194, v[208:211]
	ds_write_b128 v194, v[212:215] offset:34816
	ds_write_b128 v195, v[216:219]
	v_add_u32_e32 v194, v96, v99
	v_add_u32_e32 v195, v97, v99
	ds_write_b128 v194, v[220:223]
	ds_write_b128 v194, v[226:229] offset:34816
	ds_write_b128 v195, v[238:241]
	v_add_u32_e32 v194, v96, v100
	v_add_u32_e32 v195, v97, v100
	ds_write_b128 v194, v[242:245]
	ds_write_b128 v194, v[246:249] offset:34816
	ds_write_b128 v195, v[250:253]
	v_lshl_add_u64 v[2:3], s[76:77], 0, v[80:81]
	v_lshl_add_u64 v[6:7], v[2:3], 0, v[192:193]
	v_add_co_u32_e64 v2, s[70:71], s1, v6
	v_lshl_add_u64 v[10:11], v[82:83], 1, v[14:15]
	s_nop 0
	v_addc_co_u32_e64 v3, s[70:71], 0, v7, s[70:71]
	v_add_co_u32_e64 v6, s[70:71], s93, v6
	global_load_dwordx4 v[208:211], v[2:3], off offset:2048
	s_nop 0
	v_addc_co_u32_e64 v7, s[70:71], 0, v7, s[70:71]
	global_load_dwordx4 v[212:215], v[6:7], off
	global_load_dwordx4 v[216:219], v[10:11], off
	v_lshl_add_u64 v[2:3], s[76:77], 0, v[90:91]
	v_lshl_add_u64 v[2:3], v[84:85], 1, v[2:3]
	v_lshl_add_u64 v[6:7], v[2:3], 0, s[74:75]
	v_add_co_u32_e64 v2, s[70:71], s93, v2
	v_add_u32_e32 v91, v102, v103
	s_nop 0
	v_addc_co_u32_e64 v3, s[70:71], 0, v3, s[70:71]
	global_load_dwordx4 v[220:223], v[2:3], off offset:2048
	s_mov_b64 s[76:77], 0x2000
	global_load_dwordx4 v[226:229], v[6:7], off offset:64
	global_load_dwordx4 v[238:241], v[6:7], off offset:128
	global_load_dwordx4 v[242:245], v[6:7], off offset:192
	s_waitcnt vmcnt(0)
	v_add_u32_e32 v194, v96, v101
	v_add_u32_e32 v195, v97, v101
	ds_write_b128 v194, v[208:211]
	ds_write_b128 v194, v[212:215] offset:34816
	ds_write_b128 v195, v[216:219]
	ds_write_b16 v151, v220
	ds_write_b16_d16_hi v151, v220 offset:272
	ds_write_b16 v151, v221 offset:544
	ds_write_b16_d16_hi v151, v221 offset:816
	ds_write_b16 v151, v222 offset:1088
	ds_write_b16_d16_hi v151, v222 offset:1360
	ds_write_b16 v151, v223 offset:1632
	ds_write_b16_d16_hi v151, v223 offset:1904
	ds_write_b16 v151, v226 offset:8704
	ds_write_b16_d16_hi v151, v226 offset:8976
	ds_write_b16 v151, v227 offset:9248
	ds_write_b16_d16_hi v151, v227 offset:9520
	ds_write_b16 v151, v228 offset:9792
	ds_write_b16_d16_hi v151, v228 offset:10064
	ds_write_b16 v151, v229 offset:10336
	ds_write_b16_d16_hi v151, v229 offset:10608
	ds_write_b16 v151, v238 offset:17408
	ds_write_b16_d16_hi v151, v238 offset:17680
	ds_write_b16 v151, v239 offset:17952
	ds_write_b16_d16_hi v151, v239 offset:18224
	ds_write_b16 v151, v240 offset:18496
	ds_write_b16_d16_hi v151, v240 offset:18768
	ds_write_b16 v151, v241 offset:19040
	ds_write_b16_d16_hi v151, v241 offset:19312
	ds_write_b16 v151, v242 offset:26112
	ds_write_b16_d16_hi v151, v242 offset:26384
	ds_write_b16 v151, v243 offset:26656
	ds_write_b16_d16_hi v151, v243 offset:26928
	ds_write_b16 v151, v244 offset:27200
	ds_write_b16_d16_hi v151, v244 offset:27472
	ds_write_b16 v151, v245 offset:27744
	ds_write_b16_d16_hi v151, v245 offset:28016
	s_waitcnt lgkmcnt(0)
	s_barrier
; #define LAS __attribute__((address_space(3)))
; template <int MI, int NJ> __device__ __forceinline__ void mm_nt(f32x4 (&acc)[MI][NJ], const LAS unsigned char* A, const LAS unsigned char* B, int m0, int n0, int fr, int fq) {
; #pragma unroll
;     for (int kk = 0; kk < 4; ++kk) {
;         bf16x8 a[MI], b[NJ];
; #pragma unroll
;         for (int mi = 0; mi < MI; ++mi) a[mi] = *(const LAS bf16x8*)(A + (m0 + 16 * mi + fr) * TP + kk * 64 + fq * 16);
; #pragma unroll
;         for (int nj = 0; nj < NJ; ++nj) b[nj] = *(const LAS bf16x8*)(B + (n0 + 16 * nj + fr) * TP + kk * 64 + fq * 16);
; #pragma unroll
;         for (int mi = 0; mi < MI; ++mi)
; #pragma unroll
;             for (int nj = 0; nj < NJ; ++nj) acc[mi][nj] = __builtin_amdgcn_mfma_f32_16x16x32_bf16(a[mi], b[nj], acc[mi][nj], 0, 0, 0);
;     }
	ds_read_b128 v[18:21], v152
	ds_read_b128 v[14:17], v152 offset:4352
	ds_read_b128 v[2:5], v91 offset:34816
	ds_read_b128 v[6:9], v91 offset:39168
	ds_read_b128 v[10:13], v91 offset:43520
	ds_read_b128 v[22:25], v91 offset:47872
	s_waitcnt lgkmcnt(3)
	v_mfma_f32_16x16x32_bf16 v[26:29], v[18:21], v[2:5], 0
	s_waitcnt lgkmcnt(2)
	v_mfma_f32_16x16x32_bf16 v[30:33], v[18:21], v[6:9], 0
	v_mfma_f32_16x16x32_bf16 v[42:45], v[14:17], v[2:5], 0
	v_mfma_f32_16x16x32_bf16 v[46:49], v[14:17], v[6:9], 0
	ds_read_b128 v[6:9], v152 offset:64
	ds_read_b128 v[2:5], v152 offset:4416
	ds_read_b128 v[50:53], v91 offset:34880
	ds_read_b128 v[54:57], v91 offset:39232
	ds_read_b128 v[58:61], v91 offset:43584
	ds_read_b128 v[62:65], v91 offset:47936
	s_waitcnt lgkmcnt(7)
	v_mfma_f32_16x16x32_bf16 v[34:37], v[18:21], v[10:13], 0
	s_waitcnt lgkmcnt(6)
	v_mfma_f32_16x16x32_bf16 v[38:41], v[18:21], v[22:25], 0
	v_mfma_f32_16x16x32_bf16 v[10:13], v[14:17], v[10:13], 0
	v_mfma_f32_16x16x32_bf16 v[22:25], v[14:17], v[22:25], 0
	s_waitcnt lgkmcnt(3)
	v_mfma_f32_16x16x32_bf16 v[26:29], v[6:9], v[50:53], v[26:29]
	s_waitcnt lgkmcnt(2)
	v_mfma_f32_16x16x32_bf16 v[30:33], v[6:9], v[54:57], v[30:33]
	s_waitcnt lgkmcnt(1)
	v_mfma_f32_16x16x32_bf16 v[34:37], v[6:9], v[58:61], v[34:37]
	s_waitcnt lgkmcnt(0)
	v_mfma_f32_16x16x32_bf16 v[38:41], v[6:9], v[62:65], v[38:41]
	v_mfma_f32_16x16x32_bf16 v[42:45], v[2:5], v[50:53], v[42:45]
	v_mfma_f32_16x16x32_bf16 v[46:49], v[2:5], v[54:57], v[46:49]
	v_mfma_f32_16x16x32_bf16 v[10:13], v[2:5], v[58:61], v[10:13]
	v_mfma_f32_16x16x32_bf16 v[22:25], v[2:5], v[62:65], v[22:25]
	ds_read_b128 v[160:163], v152 offset:128
	ds_read_b128 v[164:167], v152 offset:4480
	ds_read_b128 v[50:53], v91 offset:34944
	ds_read_b128 v[54:57], v91 offset:39296
	ds_read_b128 v[58:61], v91 offset:43648
	ds_read_b128 v[62:65], v91 offset:48000
	s_waitcnt lgkmcnt(2)
	v_mfma_f32_16x16x32_bf16 v[168:171], v[160:163], v[54:57], v[30:33]
	v_mfma_f32_16x16x32_bf16 v[172:175], v[164:167], v[54:57], v[46:49]
	s_waitcnt lgkmcnt(1)
	v_mfma_f32_16x16x32_bf16 v[176:179], v[164:167], v[58:61], v[10:13]
	ds_read_b128 v[30:33], v152 offset:192
	s_nop 1
	ds_read_b128 v[10:13], v152 offset:4544
	ds_read_b128 v[46:49], v91 offset:35008
	ds_read_b128 v[180:183], v91 offset:39360
	ds_read_b128 v[184:187], v91 offset:43712
	ds_read_b128 v[188:191], v91 offset:48064
	v_mul_f32_e32 v91, v0, v104
	v_cmp_gt_f32_e64 s[70:71], s96, v91
	v_mfma_f32_16x16x32_bf16 v[26:29], v[160:163], v[50:53], v[26:29]
	s_nop 0
	v_cndmask_b32_e64 v91, 0, v234, s[70:71]
	v_fmac_f32_e32 v91, v0, v104
	v_mfma_f32_16x16x32_bf16 v[34:37], v[160:163], v[58:61], v[34:37]
	v_exp_f32_e32 v91, v91
	v_mfma_f32_16x16x32_bf16 v[42:45], v[164:167], v[50:53], v[42:45]
	s_waitcnt lgkmcnt(6)
	v_mfma_f32_16x16x32_bf16 v[22:25], v[164:167], v[62:65], v[22:25]
	v_mfma_f32_16x16x32_bf16 v[38:41], v[160:163], v[62:65], v[38:41]
	s_waitcnt lgkmcnt(3)
	v_mfma_f32_16x16x32_bf16 v[62:65], v[30:33], v[46:49], v[26:29]
	s_waitcnt lgkmcnt(2)
	v_mfma_f32_16x16x32_bf16 v[58:61], v[30:33], v[180:183], v[168:171]
	s_waitcnt lgkmcnt(1)
	v_mfma_f32_16x16x32_bf16 v[54:57], v[30:33], v[184:187], v[34:37]
	v_mfma_f32_16x16x32_bf16 v[46:49], v[10:13], v[46:49], v[42:45]
	v_mfma_f32_16x16x32_bf16 v[42:45], v[10:13], v[180:183], v[172:175]
	s_waitcnt lgkmcnt(0)
	v_mfma_f32_16x16x32_bf16 v[34:37], v[10:13], v[188:191], v[22:25]
	s_nop 2
	ds_read_b128 v[22:25], v153
	ds_read_b128 v[26:29], v153 offset:4352
	ds_read_b128 v[168:171], v153 offset:8704
	ds_read_b128 v[172:175], v153 offset:13056
	v_mfma_f32_16x16x32_bf16 v[50:53], v[30:33], v[188:191], v[38:41]
	v_mfma_f32_16x16x32_bf16 v[38:41], v[10:13], v[184:187], v[176:179]
	s_waitcnt lgkmcnt(3)
	v_mfma_f32_16x16x32_bf16 v[176:179], v[18:21], v[22:25], 0
	s_waitcnt lgkmcnt(2)
	v_mfma_f32_16x16x32_bf16 v[180:183], v[18:21], v[26:29], 0
	s_waitcnt lgkmcnt(1)
	v_mfma_f32_16x16x32_bf16 v[184:187], v[18:21], v[168:171], 0
	s_waitcnt lgkmcnt(0)
	v_mfma_f32_16x16x32_bf16 v[18:21], v[18:21], v[172:175], 0
	v_mfma_f32_16x16x32_bf16 v[22:25], v[14:17], v[22:25], 0
	v_mfma_f32_16x16x32_bf16 v[26:29], v[14:17], v[26:29], 0
	v_mfma_f32_16x16x32_bf16 v[168:171], v[14:17], v[168:171], 0
	v_mfma_f32_16x16x32_bf16 v[14:17], v[14:17], v[172:175], 0
	ds_read_b128 v[172:175], v153 offset:64
	ds_read_b128 v[188:191], v153 offset:4416
	ds_read_b128 v[200:203], v153 offset:8768
	ds_read_b128 v[204:207], v153 offset:13120
	s_waitcnt lgkmcnt(3)
	v_mfma_f32_16x16x32_bf16 v[176:179], v[6:9], v[172:175], v[176:179]
	s_waitcnt lgkmcnt(2)
	v_mfma_f32_16x16x32_bf16 v[180:183], v[6:9], v[188:191], v[180:183]
	s_waitcnt lgkmcnt(1)
	v_mfma_f32_16x16x32_bf16 v[184:187], v[6:9], v[200:203], v[184:187]
	s_waitcnt lgkmcnt(0)
	v_mfma_f32_16x16x32_bf16 v[6:9], v[6:9], v[204:207], v[18:21]
	v_mfma_f32_16x16x32_bf16 v[18:21], v[2:5], v[172:175], v[22:25]
	v_mfma_f32_16x16x32_bf16 v[22:25], v[2:5], v[188:191], v[26:29]
	v_mfma_f32_16x16x32_bf16 v[26:29], v[2:5], v[200:203], v[168:171]
	v_mfma_f32_16x16x32_bf16 v[2:5], v[2:5], v[204:207], v[14:17]
	s_nop 2
	ds_read_b128 v[14:17], v153 offset:128
	ds_read_b128 v[168:171], v153 offset:4480
	ds_read_b128 v[172:175], v153 offset:8832
	ds_read_b128 v[188:191], v153 offset:13184
	s_waitcnt lgkmcnt(3)
	v_mfma_f32_16x16x32_bf16 v[176:179], v[160:163], v[14:17], v[176:179]
	s_waitcnt lgkmcnt(2)
	v_mfma_f32_16x16x32_bf16 v[180:183], v[160:163], v[168:171], v[180:183]
	s_waitcnt lgkmcnt(1)
	v_mfma_f32_16x16x32_bf16 v[184:187], v[160:163], v[172:175], v[184:187]
	s_waitcnt lgkmcnt(0)
	v_mfma_f32_16x16x32_bf16 v[6:9], v[160:163], v[188:191], v[6:9]
	v_mfma_f32_16x16x32_bf16 v[14:17], v[164:167], v[14:17], v[18:21]
	v_mfma_f32_16x16x32_bf16 v[160:163], v[164:167], v[168:171], v[22:25]
	v_mfma_f32_16x16x32_bf16 v[168:171], v[164:167], v[172:175], v[26:29]
	v_mfma_f32_16x16x32_bf16 v[164:167], v[164:167], v[188:191], v[2:5]
	s_nop 2
	ds_read_b128 v[2:5], v153 offset:192
	ds_read_b128 v[172:175], v153 offset:4544
	ds_read_b128 v[188:191], v153 offset:8896
	ds_read_b128 v[200:203], v153 offset:13248
	s_waitcnt lgkmcnt(0)
	s_barrier
; #define LAS __attribute__((address_space(3)))
; __device__ __forceinline__ unsigned short f2bf1(float f) { return (unsigned short)(pk2(f, 0.f) & 0xffffu); }
; __device__ __forceinline__ void ret_out_unit(LAS unsigned char* lds, const bf16* Z, const bf16* RT, const float* subg, bf16* YB, int h, int n, int tid) {
;     ...
; #pragma unroll
;     for (int mi = 0; mi < 2; ++mi)
; #pragma unroll
;         for (int nj = 0; nj < 4; ++nj)
; #pragma unroll
;             for (int e = 0; e < 4; ++e) {
;                 const int i = 32 * wm + 16 * mi + 4 * fq + e, j = 64 * wn + 16 * nj + fr;
;                 const float d = (i >= j) ? exp2f((float)(i - j) * l2g) : 0.f;
;                 *(LAS unsigned short*)(Ks + i * TP + j * 2) = f2bf1(as[mi][nj][e] * d);
;             }
	v_mfma_f32_16x16x32_bf16 v[22:25], v[30:33], v[2:5], v[176:179]
	v_mfma_f32_16x16x32_bf16 v[26:29], v[30:33], v[172:175], v[180:183]
	v_mfma_f32_16x16x32_bf16 v[18:21], v[30:33], v[188:191], v[184:187]
	v_mfma_f32_16x16x32_bf16 v[30:33], v[30:33], v[200:203], v[6:9]
	v_mfma_f32_16x16x32_bf16 v[6:9], v[10:13], v[172:175], v[160:163]
	s_nop 2
	v_cndmask_b32_e64 v160, 0, v235, s[70:71]
	v_ldexp_f32 v91, v91, v160
	v_cndmask_b32_e64 v91, v91, 0, vcc
	v_mul_f32_e32 v62, v91, v62
	v_cvt_pk_bf16_f32 v62, v62, s0
	ds_write_b16 v154, v62 offset:34816
	v_mul_f32_e32 v62, v0, v105
	v_cmp_gt_f32_e64 s[70:71], s96, v62
	v_mul_f32_e32 v42, v91, v42
	v_cvt_pk_bf16_f32 v42, v42, s0
	v_cndmask_b32_e64 v62, 0, v234, s[70:71]
	v_fmac_f32_e32 v62, v0, v105
	v_exp_f32_e32 v62, v62
	v_cndmask_b32_e64 v160, 0, v235, s[70:71]
	ds_write_b16 v155, v42 offset:39168
	v_mul_f32_e32 v42, v0, v124
	v_ldexp_f32 v62, v62, v160
	v_cndmask_b32_e64 v62, v62, 0, s[6:7]
	v_mul_f32_e32 v62, v62, v63
	v_cvt_pk_bf16_f32 v62, v62, s0
	ds_write_b16 v154, v62 offset:35088
	v_mul_f32_e32 v62, v0, v106
	v_cmp_gt_f32_e64 s[70:71], s96, v62
	v_mfma_f32_16x16x32_bf16 v[2:5], v[10:13], v[2:5], v[14:17]
	s_nop 0
	v_cndmask_b32_e64 v62, 0, v234, s[70:71]
	v_fmac_f32_e32 v62, v0, v106
	v_exp_f32_e32 v62, v62
	v_cndmask_b32_e64 v63, 0, v235, s[70:71]
	v_mfma_f32_16x16x32_bf16 v[14:17], v[10:13], v[188:191], v[168:171]
	v_ldexp_f32 v62, v62, v63
	v_cndmask_b32_e64 v62, v62, 0, s[8:9]
	v_mul_f32_e32 v62, v62, v64
	v_cvt_pk_bf16_f32 v62, v62, s0
	ds_write_b16 v154, v62 offset:35360
	v_mul_f32_e32 v62, v0, v107
	v_cmp_gt_f32_e64 s[70:71], s96, v62
	v_mfma_f32_16x16x32_bf16 v[10:13], v[10:13], v[200:203], v[164:167]
	s_nop 0
	v_cndmask_b32_e64 v62, 0, v234, s[70:71]
	v_fmac_f32_e32 v62, v0, v107
	v_exp_f32_e32 v62, v62
	v_cndmask_b32_e64 v63, 0, v235, s[70:71]
	v_ldexp_f32 v62, v62, v63
	v_cndmask_b32_e64 v62, v62, 0, s[10:11]
	v_mul_f32_e32 v62, v62, v65
	v_cvt_pk_bf16_f32 v62, v62, s0
	ds_write_b16 v154, v62 offset:35632
	v_mul_f32_e32 v62, v0, v108
	v_cmp_gt_f32_e64 s[70:71], s96, v62
	s_nop 1
	v_cndmask_b32_e64 v62, 0, v234, s[70:71]
	v_fmac_f32_e32 v62, v0, v108
	v_exp_f32_e32 v62, v62
	v_cndmask_b32_e64 v63, 0, v235, s[70:71]
	v_ldexp_f32 v62, v62, v63
	v_cndmask_b32_e64 v62, v62, 0, s[12:13]
	v_mul_f32_e32 v58, v62, v58
	v_cvt_pk_bf16_f32 v58, v58, s0
	ds_write_b16 v155, v58 offset:34816
	v_mul_f32_e32 v58, v0, v109
	v_cmp_gt_f32_e64 s[70:71], s96, v58
	s_nop 1
	v_cndmask_b32_e64 v58, 0, v234, s[70:71]
	v_fmac_f32_e32 v58, v0, v109
	v_exp_f32_e32 v58, v58
	v_cndmask_b32_e64 v62, 0, v235, s[70:71]
	v_ldexp_f32 v58, v58, v62
	v_cndmask_b32_e64 v58, v58, 0, s[14:15]
	v_mul_f32_e32 v58, v58, v59
	v_cvt_pk_bf16_f32 v58, v58, s0
	ds_write_b16 v155, v58 offset:35088
	v_mul_f32_e32 v58, v0, v110
	v_cmp_gt_f32_e64 s[70:71], s96, v58
	s_nop 1
	v_cndmask_b32_e64 v58, 0, v234, s[70:71]
	v_fmac_f32_e32 v58, v0, v110
	v_exp_f32_e32 v58, v58
	v_cndmask_b32_e64 v59, 0, v235, s[70:71]
	v_ldexp_f32 v58, v58, v59
	v_cndmask_b32_e64 v58, v58, 0, s[16:17]
	v_mul_f32_e32 v58, v58, v60
	v_cvt_pk_bf16_f32 v58, v58, s0
	ds_write_b16 v155, v58 offset:35360
	v_mul_f32_e32 v58, v0, v111
	v_cmp_gt_f32_e64 s[70:71], s96, v58
	s_nop 1
	v_cndmask_b32_e64 v58, 0, v234, s[70:71]
	v_fmac_f32_e32 v58, v0, v111
	v_exp_f32_e32 v58, v58
	v_cndmask_b32_e64 v59, 0, v235, s[70:71]
	v_ldexp_f32 v58, v58, v59
	v_cndmask_b32_e64 v58, v58, 0, s[18:19]
	v_mul_f32_e32 v58, v58, v61
	v_cvt_pk_bf16_f32 v58, v58, s0
	ds_write_b16 v155, v58 offset:35632
	v_mul_f32_e32 v58, v0, v112
	v_cmp_gt_f32_e64 s[70:71], s96, v58
	s_nop 1
	v_cndmask_b32_e64 v58, 0, v234, s[70:71]
	v_fmac_f32_e32 v58, v0, v112
	v_exp_f32_e32 v58, v58
	v_cndmask_b32_e64 v59, 0, v235, s[70:71]
	v_ldexp_f32 v58, v58, v59
	v_cndmask_b32_e64 v58, v58, 0, s[20:21]
	v_mul_f32_e32 v54, v58, v54
	v_cvt_pk_bf16_f32 v54, v54, s0
	ds_write_b16 v156, v54 offset:34816
	v_mul_f32_e32 v54, v0, v113
	v_cmp_gt_f32_e64 s[70:71], s96, v54
	s_nop 1
	v_cndmask_b32_e64 v54, 0, v234, s[70:71]
	v_fmac_f32_e32 v54, v0, v113
	v_exp_f32_e32 v54, v54
	v_cndmask_b32_e64 v58, 0, v235, s[70:71]
	v_ldexp_f32 v54, v54, v58
	v_cndmask_b32_e64 v54, v54, 0, s[22:23]
	v_mul_f32_e32 v54, v54, v55
	v_cvt_pk_bf16_f32 v54, v54, s0
	ds_write_b16 v156, v54 offset:35088
	v_mul_f32_e32 v54, v0, v114
	v_cmp_gt_f32_e64 s[70:71], s96, v54
	s_nop 1
	v_cndmask_b32_e64 v54, 0, v234, s[70:71]
	v_fmac_f32_e32 v54, v0, v114
	v_exp_f32_e32 v54, v54
	v_cndmask_b32_e64 v55, 0, v235, s[70:71]
	v_ldexp_f32 v54, v54, v55
	v_cndmask_b32_e64 v54, v54, 0, s[24:25]
	v_mul_f32_e32 v54, v54, v56
	v_cvt_pk_bf16_f32 v54, v54, s0
	ds_write_b16 v156, v54 offset:35360
	v_mul_f32_e32 v54, v0, v115
	v_cmp_gt_f32_e64 s[70:71], s96, v54
	s_nop 1
	v_cndmask_b32_e64 v54, 0, v234, s[70:71]
	v_fmac_f32_e32 v54, v0, v115
	v_exp_f32_e32 v54, v54
	v_cndmask_b32_e64 v55, 0, v235, s[70:71]
	v_ldexp_f32 v54, v54, v55
	v_cndmask_b32_e64 v54, v54, 0, s[26:27]
	v_mul_f32_e32 v54, v54, v57
	v_cvt_pk_bf16_f32 v54, v54, s0
	ds_write_b16 v156, v54 offset:35632
	v_mul_f32_e32 v54, v0, v116
	v_cmp_gt_f32_e64 s[70:71], s96, v54
	s_nop 1
	v_cndmask_b32_e64 v54, 0, v234, s[70:71]
	v_fmac_f32_e32 v54, v0, v116
	v_exp_f32_e32 v54, v54
	v_cndmask_b32_e64 v55, 0, v235, s[70:71]
	v_ldexp_f32 v54, v54, v55
	v_cndmask_b32_e64 v54, v54, 0, s[28:29]
	v_mul_f32_e32 v50, v54, v50
	v_cvt_pk_bf16_f32 v50, v50, s0
	ds_write_b16 v157, v50 offset:34816
	v_mul_f32_e32 v50, v0, v117
	v_cmp_gt_f32_e64 s[70:71], s96, v50
	s_nop 1
	v_cndmask_b32_e64 v50, 0, v234, s[70:71]
	v_fmac_f32_e32 v50, v0, v117
	v_exp_f32_e32 v50, v50
	v_cndmask_b32_e64 v54, 0, v235, s[70:71]
	v_ldexp_f32 v50, v50, v54
; #define LAS __attribute__((address_space(3)))
; __device__ __forceinline__ unsigned short f2bf1(float f) { return (unsigned short)(pk2(f, 0.f) & 0xffffu); }
; __device__ __forceinline__ void ret_out_unit(LAS unsigned char* lds, const bf16* Z, const bf16* RT, const float* subg, bf16* YB, int h, int n, int tid) {
;     ...
; #pragma unroll
;     for (int mi = 0; mi < 2; ++mi)
; #pragma unroll
;         for (int nj = 0; nj < 4; ++nj)
; #pragma unroll
;             for (int e = 0; e < 4; ++e) {
;                 const int i = 32 * wm + 16 * mi + 4 * fq + e, j = 64 * wn + 16 * nj + fr;
;                 const float d = (i >= j) ? exp2f((float)(i - j) * l2g) : 0.f;
;                 *(LAS unsigned short*)(Ks + i * TP + j * 2) = f2bf1(as[mi][nj][e] * d);
;             }
;     __syncthreads();
	v_cndmask_b32_e64 v50, v50, 0, s[30:31]
	v_mul_f32_e32 v50, v50, v51
	v_cvt_pk_bf16_f32 v50, v50, s0
	ds_write_b16 v157, v50 offset:35088
	v_mul_f32_e32 v50, v0, v118
	v_cmp_gt_f32_e64 s[70:71], s96, v50
	s_nop 1
	v_cndmask_b32_e64 v50, 0, v234, s[70:71]
	v_fmac_f32_e32 v50, v0, v118
	v_exp_f32_e32 v50, v50
	v_cndmask_b32_e64 v51, 0, v235, s[70:71]
	v_ldexp_f32 v50, v50, v51
	v_cndmask_b32_e64 v50, v50, 0, s[34:35]
	v_mul_f32_e32 v50, v50, v52
	v_cvt_pk_bf16_f32 v50, v50, s0
	ds_write_b16 v157, v50 offset:35360
	v_mul_f32_e32 v50, v0, v119
	v_cmp_gt_f32_e64 s[70:71], s96, v50
	s_nop 1
	v_cndmask_b32_e64 v50, 0, v234, s[70:71]
	v_fmac_f32_e32 v50, v0, v119
	v_exp_f32_e32 v50, v50
	v_cndmask_b32_e64 v51, 0, v235, s[70:71]
	v_ldexp_f32 v50, v50, v51
	v_cndmask_b32_e64 v50, v50, 0, s[36:37]
	v_mul_f32_e32 v50, v50, v53
	v_cvt_pk_bf16_f32 v50, v50, s0
	ds_write_b16 v157, v50 offset:35632
	v_mul_f32_e32 v50, v0, v120
	v_cmp_gt_f32_e64 s[70:71], s96, v50
	s_nop 1
	v_cndmask_b32_e64 v50, 0, v234, s[70:71]
	v_fmac_f32_e32 v50, v0, v120
	v_exp_f32_e32 v50, v50
	v_cndmask_b32_e64 v51, 0, v235, s[70:71]
	v_ldexp_f32 v50, v50, v51
	v_cndmask_b32_e64 v50, v50, 0, s[38:39]
	v_mul_f32_e32 v46, v50, v46
	v_cvt_pk_bf16_f32 v46, v46, s0
	ds_write_b16 v154, v46 offset:39168
	v_mul_f32_e32 v46, v0, v121
	v_cmp_gt_f32_e64 s[70:71], s96, v46
	s_nop 1
	v_cndmask_b32_e64 v46, 0, v234, s[70:71]
	v_fmac_f32_e32 v46, v0, v121
	v_exp_f32_e32 v46, v46
	v_cndmask_b32_e64 v50, 0, v235, s[70:71]
	v_ldexp_f32 v46, v46, v50
	v_cndmask_b32_e64 v46, v46, 0, s[40:41]
	v_mul_f32_e32 v46, v46, v47
	v_cvt_pk_bf16_f32 v46, v46, s0
	ds_write_b16 v154, v46 offset:39440
	v_mul_f32_e32 v46, v0, v122
	v_cmp_gt_f32_e64 s[70:71], s96, v46
	s_nop 1
	v_cndmask_b32_e64 v46, 0, v234, s[70:71]
	v_fmac_f32_e32 v46, v0, v122
	v_exp_f32_e32 v46, v46
	v_cndmask_b32_e64 v47, 0, v235, s[70:71]
	v_ldexp_f32 v46, v46, v47
	v_cndmask_b32_e64 v46, v46, 0, s[42:43]
	v_mul_f32_e32 v46, v46, v48
	v_cvt_pk_bf16_f32 v46, v46, s0
	ds_write_b16 v154, v46 offset:39712
	v_mul_f32_e32 v46, v0, v123
	v_cmp_gt_f32_e64 s[70:71], s96, v46
	s_nop 1
	v_cndmask_b32_e64 v46, 0, v234, s[70:71]
	v_fmac_f32_e32 v46, v0, v123
	v_exp_f32_e32 v46, v46
	v_cndmask_b32_e64 v47, 0, v235, s[70:71]
	v_cmp_gt_f32_e64 s[70:71], s96, v42
	v_ldexp_f32 v46, v46, v47
	s_nop 0
	v_cndmask_b32_e64 v42, 0, v234, s[70:71]
	v_fmac_f32_e32 v42, v0, v124
	v_cndmask_b32_e64 v46, v46, 0, s[44:45]
	v_exp_f32_e32 v42, v42
	v_mul_f32_e32 v46, v46, v49
	v_cvt_pk_bf16_f32 v46, v46, s0
	ds_write_b16 v154, v46 offset:39984
	v_cndmask_b32_e64 v46, 0, v235, s[70:71]
	v_ldexp_f32 v42, v42, v46
	v_cndmask_b32_e64 v42, v42, 0, s[46:47]
	v_mul_f32_e32 v42, v42, v43
	v_cvt_pk_bf16_f32 v42, v42, s0
	ds_write_b16 v155, v42 offset:39440
	v_mul_f32_e32 v42, v0, v125
	v_cmp_gt_f32_e64 s[70:71], s96, v42
	s_nop 1
	v_cndmask_b32_e64 v42, 0, v234, s[70:71]
	v_fmac_f32_e32 v42, v0, v125
	v_exp_f32_e32 v42, v42
	v_cndmask_b32_e64 v43, 0, v235, s[70:71]
	v_ldexp_f32 v42, v42, v43
	v_cndmask_b32_e64 v42, v42, 0, s[48:49]
	v_mul_f32_e32 v42, v42, v44
	v_cvt_pk_bf16_f32 v42, v42, s0
	ds_write_b16 v155, v42 offset:39712
	v_mul_f32_e32 v42, v0, v126
	v_cmp_gt_f32_e64 s[70:71], s96, v42
	s_nop 1
	v_cndmask_b32_e64 v42, 0, v234, s[70:71]
	v_fmac_f32_e32 v42, v0, v126
	v_exp_f32_e32 v42, v42
	v_cndmask_b32_e64 v43, 0, v235, s[70:71]
	v_ldexp_f32 v42, v42, v43
	v_cndmask_b32_e64 v42, v42, 0, s[50:51]
	v_mul_f32_e32 v42, v42, v45
	v_cvt_pk_bf16_f32 v42, v42, s0
	ds_write_b16 v155, v42 offset:39984
	v_mul_f32_e32 v42, v0, v127
	v_cmp_gt_f32_e64 s[70:71], s96, v42
	s_nop 1
	v_cndmask_b32_e64 v42, 0, v234, s[70:71]
	v_fmac_f32_e32 v42, v0, v127
	v_exp_f32_e32 v42, v42
	v_cndmask_b32_e64 v43, 0, v235, s[70:71]
	v_ldexp_f32 v42, v42, v43
	v_cndmask_b32_e64 v42, v42, 0, s[52:53]
	v_mul_f32_e32 v38, v42, v38
	v_cvt_pk_bf16_f32 v38, v38, s0
	ds_write_b16 v156, v38 offset:39168
	v_mul_f32_e32 v38, v0, v128
	v_cmp_gt_f32_e64 s[70:71], s96, v38
	s_nop 1
	v_cndmask_b32_e64 v38, 0, v234, s[70:71]
	v_fmac_f32_e32 v38, v0, v128
	v_exp_f32_e32 v38, v38
	v_cndmask_b32_e64 v42, 0, v235, s[70:71]
	v_ldexp_f32 v38, v38, v42
	v_cndmask_b32_e64 v38, v38, 0, s[54:55]
	v_mul_f32_e32 v38, v38, v39
	v_cvt_pk_bf16_f32 v38, v38, s0
	ds_write_b16 v156, v38 offset:39440
	v_mul_f32_e32 v38, v0, v129
	v_cmp_gt_f32_e64 s[70:71], s96, v38
	s_nop 1
	v_cndmask_b32_e64 v38, 0, v234, s[70:71]
	v_fmac_f32_e32 v38, v0, v129
	v_exp_f32_e32 v38, v38
	v_cndmask_b32_e64 v39, 0, v235, s[70:71]
	v_ldexp_f32 v38, v38, v39
	v_cndmask_b32_e64 v38, v38, 0, s[56:57]
	v_mul_f32_e32 v38, v38, v40
	v_cvt_pk_bf16_f32 v38, v38, s0
	ds_write_b16 v156, v38 offset:39712
	v_mul_f32_e32 v38, v0, v130
	v_cmp_gt_f32_e64 s[70:71], s96, v38
	s_nop 1
	v_cndmask_b32_e64 v38, 0, v234, s[70:71]
	v_fmac_f32_e32 v38, v0, v130
	v_exp_f32_e32 v38, v38
	v_cndmask_b32_e64 v39, 0, v235, s[70:71]
	v_ldexp_f32 v38, v38, v39
	v_cndmask_b32_e64 v38, v38, 0, s[58:59]
	v_mul_f32_e32 v38, v38, v41
	v_cvt_pk_bf16_f32 v38, v38, s0
	ds_write_b16 v156, v38 offset:39984
	v_mul_f32_e32 v38, v0, v131
	v_cmp_gt_f32_e64 s[70:71], s96, v38
	s_nop 1
	v_cndmask_b32_e64 v38, 0, v234, s[70:71]
	v_fmac_f32_e32 v38, v0, v131
	v_exp_f32_e32 v38, v38
	v_cndmask_b32_e64 v39, 0, v235, s[70:71]
	v_ldexp_f32 v38, v38, v39
	v_cndmask_b32_e64 v38, v38, 0, s[60:61]
	v_mul_f32_e32 v34, v38, v34
	v_cvt_pk_bf16_f32 v34, v34, s0
	ds_write_b16 v157, v34 offset:39168
	v_mul_f32_e32 v34, v0, v132
	v_cmp_gt_f32_e64 s[70:71], s96, v34
	s_nop 1
	v_cndmask_b32_e64 v34, 0, v234, s[70:71]
	v_fmac_f32_e32 v34, v0, v132
	v_exp_f32_e32 v34, v34
	v_cndmask_b32_e64 v38, 0, v235, s[70:71]
	v_ldexp_f32 v34, v34, v38
	v_cndmask_b32_e64 v34, v34, 0, s[62:63]
	v_mul_f32_e32 v34, v34, v35
	v_cvt_pk_bf16_f32 v34, v34, s0
	ds_write_b16 v157, v34 offset:39440
	v_mul_f32_e32 v34, v0, v133
	v_cmp_gt_f32_e64 s[70:71], s96, v34
	s_nop 1
	v_cndmask_b32_e64 v34, 0, v234, s[70:71]
	v_fmac_f32_e32 v34, v0, v133
	v_exp_f32_e32 v34, v34
	v_cndmask_b32_e64 v35, 0, v235, s[70:71]
	v_ldexp_f32 v34, v34, v35
	v_cndmask_b32_e64 v34, v34, 0, s[64:65]
	v_mul_f32_e32 v34, v34, v36
	v_cvt_pk_bf16_f32 v34, v34, s0
	ds_write_b16 v157, v34 offset:39712
	v_mul_f32_e32 v34, v0, v134
	v_cmp_gt_f32_e64 s[70:71], s96, v34
	s_nop 1
	v_cndmask_b32_e64 v34, 0, v234, s[70:71]
	v_fmac_f32_e32 v34, v0, v134
	v_exp_f32_e32 v34, v34
	v_cndmask_b32_e64 v35, 0, v235, s[70:71]
	v_ldexp_f32 v34, v34, v35
	v_cndmask_b32_e64 v34, v34, 0, s[66:67]
	v_mul_f32_e32 v34, v34, v37
	v_cvt_pk_bf16_f32 v34, v34, s0
	ds_write_b16 v157, v34 offset:39984
	s_waitcnt lgkmcnt(0)
	s_barrier
; #define LAS __attribute__((address_space(3)))
; __device__ __forceinline__ void ret_out_unit(LAS unsigned char* lds, const bf16* Z, const bf16* RT, const float* subg, bf16* YB, int h, int n, int tid) {
;     ...
;     mm_nt<2, 4>(as, Ks, VT, 32 * wm, 64 * wn, fr, fq);
;     __syncthreads();
;     LAS float* OF = (LAS float*)lds;
; #pragma unroll
;     for (int mi = 0; mi < 2; ++mi)
; #pragma unroll
;         for (int e = 0; e < 4; ++e) {
;             const int i = 32 * wm + 16 * mi + 4 * fq + e; const float xi = exp2f((float)(i + 1) * l2g);
; #pragma unroll
;             for (int nj = 0; nj < 4; ++nj) OF[i * 132 + 64 * wn + 16 * nj + fr] = as[mi][nj][e] + xi * ac[mi][nj][e];
;         }
	ds_read_b128 v[34:37], v152 offset:34816
	ds_read_b128 v[38:41], v152 offset:39168
	ds_read_b128 v[42:45], v158
	ds_read_b128 v[46:49], v158 offset:4352
	ds_read_b128 v[50:53], v158 offset:8704
	ds_read_b128 v[54:57], v158 offset:13056
	s_waitcnt lgkmcnt(3)
	v_mfma_f32_16x16x32_bf16 v[58:61], v[34:37], v[42:45], 0
	s_waitcnt lgkmcnt(2)
	v_mfma_f32_16x16x32_bf16 v[62:65], v[34:37], v[46:49], 0
	s_waitcnt lgkmcnt(1)
	v_mfma_f32_16x16x32_bf16 v[160:163], v[34:37], v[50:53], 0
	s_waitcnt lgkmcnt(0)
	v_mfma_f32_16x16x32_bf16 v[34:37], v[34:37], v[54:57], 0
	v_mfma_f32_16x16x32_bf16 v[42:45], v[38:41], v[42:45], 0
	v_mfma_f32_16x16x32_bf16 v[46:49], v[38:41], v[46:49], 0
	v_mfma_f32_16x16x32_bf16 v[50:53], v[38:41], v[50:53], 0
	v_mfma_f32_16x16x32_bf16 v[38:41], v[38:41], v[54:57], 0
	ds_read_b128 v[54:57], v152 offset:34880
	ds_read_b128 v[164:167], v152 offset:39232
	ds_read_b128 v[168:171], v158 offset:64
	ds_read_b128 v[172:175], v158 offset:4416
	ds_read_b128 v[176:179], v158 offset:8768
	ds_read_b128 v[180:183], v158 offset:13120
	s_waitcnt lgkmcnt(3)
	v_mfma_f32_16x16x32_bf16 v[58:61], v[54:57], v[168:171], v[58:61]
	s_waitcnt lgkmcnt(2)
	v_mfma_f32_16x16x32_bf16 v[62:65], v[54:57], v[172:175], v[62:65]
	s_waitcnt lgkmcnt(1)
	v_mfma_f32_16x16x32_bf16 v[160:163], v[54:57], v[176:179], v[160:163]
	s_waitcnt lgkmcnt(0)
	v_mfma_f32_16x16x32_bf16 v[34:37], v[54:57], v[180:183], v[34:37]
	v_mfma_f32_16x16x32_bf16 v[42:45], v[164:167], v[168:171], v[42:45]
	v_mfma_f32_16x16x32_bf16 v[46:49], v[164:167], v[172:175], v[46:49]
	v_mfma_f32_16x16x32_bf16 v[50:53], v[164:167], v[176:179], v[50:53]
	v_mfma_f32_16x16x32_bf16 v[38:41], v[164:167], v[180:183], v[38:41]
	ds_read_b128 v[54:57], v152 offset:34944
	ds_read_b128 v[164:167], v152 offset:39296
	ds_read_b128 v[168:171], v158 offset:128
	ds_read_b128 v[172:175], v158 offset:4480
	ds_read_b128 v[176:179], v158 offset:8832
	ds_read_b128 v[180:183], v158 offset:13184
	s_waitcnt lgkmcnt(3)
	v_mfma_f32_16x16x32_bf16 v[58:61], v[54:57], v[168:171], v[58:61]
	s_waitcnt lgkmcnt(2)
	v_mfma_f32_16x16x32_bf16 v[62:65], v[54:57], v[172:175], v[62:65]
	s_waitcnt lgkmcnt(1)
	v_mfma_f32_16x16x32_bf16 v[160:163], v[54:57], v[176:179], v[160:163]
	s_waitcnt lgkmcnt(0)
	v_mfma_f32_16x16x32_bf16 v[34:37], v[54:57], v[180:183], v[34:37]
	v_mfma_f32_16x16x32_bf16 v[42:45], v[164:167], v[168:171], v[42:45]
	v_mfma_f32_16x16x32_bf16 v[46:49], v[164:167], v[172:175], v[46:49]
	v_mfma_f32_16x16x32_bf16 v[50:53], v[164:167], v[176:179], v[50:53]
	v_mfma_f32_16x16x32_bf16 v[38:41], v[164:167], v[180:183], v[38:41]
	ds_read_b128 v[54:57], v152 offset:35008
	ds_read_b128 v[164:167], v152 offset:39360
	ds_read_b128 v[168:171], v158 offset:192
	ds_read_b128 v[172:175], v158 offset:4544
	ds_read_b128 v[176:179], v158 offset:8896
	ds_read_b128 v[180:183], v158 offset:13248
	s_waitcnt lgkmcnt(0)
	s_barrier
	v_mfma_f32_16x16x32_bf16 v[58:61], v[54:57], v[168:171], v[58:61]
	v_mfma_f32_16x16x32_bf16 v[62:65], v[54:57], v[172:175], v[62:65]
	v_mfma_f32_16x16x32_bf16 v[160:163], v[54:57], v[176:179], v[160:163]
	v_mfma_f32_16x16x32_bf16 v[54:57], v[54:57], v[180:183], v[34:37]
	v_mfma_f32_16x16x32_bf16 v[34:37], v[164:167], v[176:179], v[50:53]
	s_nop 2
	v_mul_f32_e32 v50, v0, v135
	v_cmp_gt_f32_e64 s[70:71], s96, v50
	v_mfma_f32_16x16x32_bf16 v[42:45], v[164:167], v[168:171], v[42:45]
	s_nop 0
	v_cndmask_b32_e64 v50, 0, v234, s[70:71]
	v_fmac_f32_e32 v50, v0, v135
	v_exp_f32_e32 v50, v50
	v_cndmask_b32_e64 v51, 0, v235, s[70:71]
	v_mfma_f32_16x16x32_bf16 v[46:49], v[164:167], v[172:175], v[46:49]
	v_ldexp_f32 v50, v50, v51
	v_fma_f32 v22, v50, v22, v58
	v_fma_f32 v26, v50, v26, v62
	ds_write2_b32 v159, v22, v26 offset1:16
	v_fma_f32 v18, v50, v18, v160
	v_fma_f32 v22, v50, v30, v54
	ds_write2_b32 v159, v18, v22 offset0:32 offset1:48
	v_mul_f32_e32 v18, v0, v136
	v_cmp_gt_f32_e64 s[70:71], s96, v18
	v_mfma_f32_16x16x32_bf16 v[38:41], v[164:167], v[180:183], v[38:41]
	s_nop 0
	v_cndmask_b32_e64 v18, 0, v234, s[70:71]
	v_fmac_f32_e32 v18, v0, v136
	v_exp_f32_e32 v18, v18
	v_cndmask_b32_e64 v22, 0, v235, s[70:71]
	v_ldexp_f32 v18, v18, v22
	v_fma_f32 v22, v18, v23, v59
	v_fma_f32 v23, v18, v27, v63
	v_fma_f32 v19, v18, v19, v161
	v_fma_f32 v18, v18, v31, v55
	ds_write2_b32 v159, v19, v18 offset0:164 offset1:180
	v_mul_f32_e32 v18, v0, v137
	v_cmp_gt_f32_e64 s[70:71], s96, v18
	ds_write2_b32 v159, v22, v23 offset0:132 offset1:148
	v_add_u32_e32 v23, 0x400, v159
	v_cndmask_b32_e64 v18, 0, v234, s[70:71]
	v_fmac_f32_e32 v18, v0, v137
	v_exp_f32_e32 v18, v18
	v_cndmask_b32_e64 v19, 0, v235, s[70:71]
	v_ldexp_f32 v18, v18, v19
	v_fma_f32 v19, v18, v24, v60
	v_fma_f32 v22, v18, v28, v64
	ds_write2_b32 v23, v19, v22 offset0:8 offset1:24
	v_fma_f32 v19, v18, v20, v162
	v_fma_f32 v18, v18, v32, v56
	ds_write2_b32 v23, v19, v18 offset0:40 offset1:56
	v_mul_f32_e32 v18, v0, v138
	v_cmp_gt_f32_e64 s[70:71], s96, v18
	s_nop 1
	v_cndmask_b32_e64 v18, 0, v234, s[70:71]
	v_fmac_f32_e32 v18, v0, v138
	v_exp_f32_e32 v18, v18
	v_cndmask_b32_e64 v19, 0, v235, s[70:71]
	v_ldexp_f32 v18, v18, v19
	v_fmac_f32_e32 v61, v18, v25
	v_fmac_f32_e32 v65, v18, v29
	v_fmac_f32_e32 v163, v18, v21
	v_fmac_f32_e32 v57, v18, v33
	v_mul_f32_e32 v18, v0, v139
	v_cmp_gt_f32_e64 s[70:71], s96, v18
	ds_write2_b32 v23, v61, v65 offset0:140 offset1:156
	ds_write2_b32 v23, v163, v57 offset0:172 offset1:188
	v_cndmask_b32_e64 v18, 0, v234, s[70:71]
	v_fmac_f32_e32 v18, v0, v139
	v_exp_f32_e32 v18, v18
	v_cndmask_b32_e64 v19, 0, v235, s[70:71]
	v_ldexp_f32 v18, v18, v19
	v_fma_f32 v2, v18, v2, v42
	v_fma_f32 v6, v18, v6, v46
	v_add_u32_e32 v19, 0x2000, v159
; __device__ __forceinline__ float sigm(float x) { return __builtin_amdgcn_rcpf(1.0f + __expf(-x)); }
; __device__ __forceinline__ float bflo(unsigned w) { return __uint_as_float(w << 16); }
; __device__ __forceinline__ float bfhi(unsigned w) { return __uint_as_float(w & 0xffff0000u); }
; #define LAS __attribute__((address_space(3)))
; __device__ __forceinline__ unsigned pk2(float lo, float hi) { return pg8::cvt_pk_bf16(lo, hi); }
; __device__ __forceinline__ void ret_out_unit(LAS unsigned char* lds, const bf16* Z, const bf16* RT, const float* subg, bf16* YB, int h, int n, int tid) {
;     ...
;             for (int nj = 0; nj < 4; ++nj) OF[i * 132 + 64 * wn + 16 * nj + fr] = as[mi][nj][e] + xi * ac[mi][nj][e];
;         }
;     __syncthreads();
;     const f32x2 g2 = *(const f32x2*)(subg + 2 * lane);
; #pragma unroll 4
;     for (int rr = 0; rr < 16; ++rr) {
;         const int i = wid * 16 + rr;
;         const f32x2 x = *(const LAS f32x2*)(OF + i * 132 + 2 * lane);
;         const float r = rsqrtf(wave_sum(x.x * x.x + x.y * x.y) * (1.f / 128.f) + EPS);
;         const size_t row = (size_t)(n * 128 + i);
;         const unsigned gw = *(const unsigned*)(Z + row * NIN + ZGR + h * 128 + 2 * lane);
;         const float ga = bflo(gw), gb = bfhi(gw);
;         *(unsigned*)(YB + row * 1024 + h * 128 + 2 * lane) = pk2(x.x * r * g2.x * (ga * sigm(ga)), x.y * r * g2.y * (gb * sigm(gb)));
;     }
	ds_write2_b32 v19, v2, v6 offset0:64 offset1:80
	v_fma_f32 v2, v18, v14, v34
	v_fma_f32 v6, v18, v10, v38
	ds_write2_b32 v19, v2, v6 offset0:96 offset1:112
	v_mul_f32_e32 v2, v0, v140
	v_cmp_gt_f32_e64 s[70:71], s96, v2
	s_nop 1
	v_cndmask_b32_e64 v2, 0, v234, s[70:71]
	v_fmac_f32_e32 v2, v0, v140
	v_exp_f32_e32 v2, v2
	v_cndmask_b32_e64 v6, 0, v235, s[70:71]
	v_ldexp_f32 v2, v2, v6
	v_fma_f32 v3, v2, v3, v43
	v_fma_f32 v6, v2, v7, v47
	ds_write2_b32 v19, v3, v6 offset0:196 offset1:212
	v_fma_f32 v3, v2, v15, v35
	v_fma_f32 v2, v2, v11, v39
	ds_write2_b32 v19, v3, v2 offset0:228 offset1:244
	v_mul_f32_e32 v2, v0, v141
	v_cmp_gt_f32_e64 s[70:71], s96, v2
	v_add_u32_e32 v6, 0x2400, v159
	s_nop 0
	v_cndmask_b32_e64 v2, 0, v234, s[70:71]
	v_fmac_f32_e32 v2, v0, v141
	v_exp_f32_e32 v2, v2
	v_cndmask_b32_e64 v3, 0, v235, s[70:71]
	v_ldexp_f32 v2, v2, v3
	v_fma_f32 v3, v2, v4, v44
	v_fma_f32 v4, v2, v8, v48
	ds_write2_b32 v6, v3, v4 offset0:72 offset1:88
	v_fma_f32 v3, v2, v16, v36
	v_fma_f32 v2, v2, v12, v40
	ds_write2_b32 v6, v3, v2 offset0:104 offset1:120
	v_mul_f32_e32 v2, v0, v142
	v_cmp_gt_f32_e64 s[70:71], s96, v2
	s_nop 1
	v_cndmask_b32_e64 v2, 0, v234, s[70:71]
	v_fmac_f32_e32 v2, v0, v142
	v_exp_f32_e32 v0, v2
	v_cndmask_b32_e64 v2, 0, v235, s[70:71]
	v_ldexp_f32 v0, v0, v2
	v_fmac_f32_e32 v45, v0, v5
	v_fmac_f32_e32 v49, v0, v9
	v_fmac_f32_e32 v37, v0, v17
	v_fmac_f32_e32 v41, v0, v13
	ds_write2_b32 v6, v45, v49 offset0:204 offset1:220
	ds_write2_b32 v6, v37, v41 offset0:236 offset1:252
	s_waitcnt lgkmcnt(0)
	s_barrier
	v_and_b32_e32 v2, 15, v224
	v_lshrrev_b32_e32 v3, 4, v224
	v_readlane_b32 s70, v254, 25
	s_and_b32 s71, s0, 0x7f
	s_lshl_b32 s71, s71, 7
	s_lshl_b32 s1, s70, 4
	s_add_i32 s71, s71, s1
	v_add_u32_e32 v4, s71, v3
	v_add_u32_e32 v5, s1, v3
	v_mul_u32_u24_e32 v5, 0x210, v5
	v_lshl_add_u32 v226, v2, 5, v5
	s_lshr_b32 s1, s0, 7
	s_lshl_b32 s1, s1, 8
	v_lshl_add_u32 v6, v2, 4, s1
	v_readlane_b32 s70, v254, 23
	v_readlane_b32 s71, v254, 24
	s_load_dwordx2 s[70:71], s[70:71], 0xe0
	v_mul_lo_u32 v7, v4, s33
	s_mov_b32 s1, 0x11203000
	v_add3_u32 v7, v7, v6, s1
	v_lshlrev_b32_e32 v8, 11, v4
	s_mov_b32 s1, 0x2d200000
	v_add3_u32 v227, v8, v6, s1
	v_lshlrev_b32_e32 v8, 5, v2
	v_lshlrev_b32_e32 v9, 3, v224
	v_sub_u32_e32 v8, v8, v9
	v_ashrrev_i32_e32 v9, 31, v8
	v_lshl_add_u64 v[8:9], v[86:87], 0, v[8:9]
	global_load_dwordx4 v[238:241], v[8:9], off
	global_load_dwordx4 v[242:245], v[8:9], off offset:16
	s_waitcnt lgkmcnt(0)
	global_load_dwordx4 v[208:211], v7, s[70:71]
	v_add_u32_e32 v7, 0x16000, v7
	global_load_dwordx4 v[212:215], v7, s[70:71]
	v_add_u32_e32 v7, 0x16000, v7
	global_load_dwordx4 v[216:219], v7, s[70:71]
	v_add_u32_e32 v7, 0x16000, v7
	global_load_dwordx4 v[220:223], v7, s[70:71]
	ds_read_b128 v[2:5], v226
	ds_read_b128 v[6:9], v226 offset:16
	s_waitcnt lgkmcnt(0)
	v_mul_f32_e32 v0, v2, v2
	v_fmac_f32_e32 v0, v3, v3
	v_fmac_f32_e32 v0, v4, v4
	v_fmac_f32_e32 v0, v5, v5
	v_fmac_f32_e32 v0, v6, v6
	v_fmac_f32_e32 v0, v7, v7
	v_fmac_f32_e32 v0, v8, v8
	v_fmac_f32_e32 v0, v9, v9
	s_nop 1
	v_add_f32_dpp v0, v0, v0 quad_perm:[1,0,3,2] row_mask:0xf bank_mask:0xf
	s_nop 1
	v_add_f32_dpp v0, v0, v0 quad_perm:[2,3,0,1] row_mask:0xf bank_mask:0xf
	s_nop 1
	v_add_f32_dpp v0, v0, v0 row_half_mirror row_mask:0xf bank_mask:0xf
	s_nop 1
	v_add_f32_dpp v0, v0, v0 row_mirror row_mask:0xf bank_mask:0xf
	v_fmamk_f32 v0, v0, 0x3c000000, v232
	v_rsq_f32_e32 v0, v0
	s_waitcnt vmcnt(3)
	v_lshlrev_b32_e32 v246, 16, v208
	v_and_b32_e32 v247, 0xffff0000, v208
	v_lshlrev_b32_e32 v248, 16, v209
	v_and_b32_e32 v249, 0xffff0000, v209
	v_lshlrev_b32_e32 v250, 16, v210
	v_and_b32_e32 v251, 0xffff0000, v210
	v_lshlrev_b32_e32 v252, 16, v211
	v_and_b32_e32 v253, 0xffff0000, v211
	v_mul_f32_e32 v10, 0xbfb8aa3b, v246
	v_mul_f32_e32 v11, 0xbfb8aa3b, v247
	v_mul_f32_e32 v12, 0xbfb8aa3b, v248
	v_mul_f32_e32 v13, 0xbfb8aa3b, v249
	v_mul_f32_e32 v14, 0xbfb8aa3b, v250
	v_mul_f32_e32 v15, 0xbfb8aa3b, v251
	v_mul_f32_e32 v228, 0xbfb8aa3b, v252
	v_mul_f32_e32 v229, 0xbfb8aa3b, v253
	v_exp_f32_e32 v10, v10
	v_exp_f32_e32 v11, v11
	v_exp_f32_e32 v12, v12
	v_exp_f32_e32 v13, v13
	v_exp_f32_e32 v14, v14
	v_exp_f32_e32 v15, v15
	v_exp_f32_e32 v228, v228
	v_exp_f32_e32 v229, v229
	v_add_f32_e32 v10, 1.0, v10
	v_add_f32_e32 v11, 1.0, v11
	v_add_f32_e32 v12, 1.0, v12
	v_add_f32_e32 v13, 1.0, v13
	v_add_f32_e32 v14, 1.0, v14
	v_add_f32_e32 v15, 1.0, v15
	v_add_f32_e32 v228, 1.0, v228
	v_add_f32_e32 v229, 1.0, v229
	v_rcp_f32_e32 v10, v10
	v_rcp_f32_e32 v11, v11
	v_rcp_f32_e32 v12, v12
	v_rcp_f32_e32 v13, v13
	v_rcp_f32_e32 v14, v14
	v_rcp_f32_e32 v15, v15
	v_rcp_f32_e32 v228, v228
	v_rcp_f32_e32 v229, v229
	v_pk_mul_f32 v[2:3], v[2:3], v[0:1] op_sel_hi:[1,0]
	v_pk_mul_f32 v[4:5], v[4:5], v[0:1] op_sel_hi:[1,0]
	v_pk_mul_f32 v[6:7], v[6:7], v[0:1] op_sel_hi:[1,0]
	v_pk_mul_f32 v[8:9], v[8:9], v[0:1] op_sel_hi:[1,0]
	v_pk_mul_f32 v[2:3], v[238:239], v[2:3]
	v_pk_mul_f32 v[4:5], v[240:241], v[4:5]
	v_pk_mul_f32 v[6:7], v[242:243], v[6:7]
	v_pk_mul_f32 v[8:9], v[244:245], v[8:9]
	v_pk_mul_f32 v[246:247], v[10:11], v[246:247]
	v_pk_mul_f32 v[248:249], v[12:13], v[248:249]
	v_pk_mul_f32 v[250:251], v[14:15], v[250:251]
	v_pk_mul_f32 v[252:253], v[228:229], v[252:253]
	v_pk_mul_f32 v[2:3], v[246:247], v[2:3]
	v_pk_mul_f32 v[4:5], v[248:249], v[4:5]
	v_pk_mul_f32 v[6:7], v[250:251], v[6:7]
	v_pk_mul_f32 v[8:9], v[252:253], v[8:9]
	v_cvt_pk_bf16_f32 v10, v2, v3
	v_cvt_pk_bf16_f32 v11, v4, v5
	v_cvt_pk_bf16_f32 v12, v6, v7
	v_cvt_pk_bf16_f32 v13, v8, v9
	global_store_dwordx4 v227, v[10:13], s[70:71]
	v_add_u32_e32 v227, 0x2000, v227
	ds_read_b128 v[2:5], v226 offset:2112
	ds_read_b128 v[6:9], v226 offset:2128
	s_waitcnt lgkmcnt(0)
; __device__ __forceinline__ float sigm(float x) { return __builtin_amdgcn_rcpf(1.0f + __expf(-x)); }
; __device__ __forceinline__ float bflo(unsigned w) { return __uint_as_float(w << 16); }
; __device__ __forceinline__ float bfhi(unsigned w) { return __uint_as_float(w & 0xffff0000u); }
; #define LAS __attribute__((address_space(3)))
; __device__ __forceinline__ unsigned pk2(float lo, float hi) { return pg8::cvt_pk_bf16(lo, hi); }
; __device__ __forceinline__ void ret_out_unit(LAS unsigned char* lds, const bf16* Z, const bf16* RT, const float* subg, bf16* YB, int h, int n, int tid) {
;     ...
;     for (int rr = 0; rr < 16; ++rr) {
;         const int i = wid * 16 + rr;
;         const f32x2 x = *(const LAS f32x2*)(OF + i * 132 + 2 * lane);
;         const float r = rsqrtf(wave_sum(x.x * x.x + x.y * x.y) * (1.f / 128.f) + EPS);
;         const size_t row = (size_t)(n * 128 + i);
;         const unsigned gw = *(const unsigned*)(Z + row * NIN + ZGR + h * 128 + 2 * lane);
;         const float ga = bflo(gw), gb = bfhi(gw);
;         *(unsigned*)(YB + row * 1024 + h * 128 + 2 * lane) = pk2(x.x * r * g2.x * (ga * sigm(ga)), x.y * r * g2.y * (gb * sigm(gb)));
;     }
	v_mul_f32_e32 v0, v2, v2
	v_fmac_f32_e32 v0, v3, v3
	v_fmac_f32_e32 v0, v4, v4
	v_fmac_f32_e32 v0, v5, v5
	v_fmac_f32_e32 v0, v6, v6
	v_fmac_f32_e32 v0, v7, v7
	v_fmac_f32_e32 v0, v8, v8
	v_fmac_f32_e32 v0, v9, v9
	s_nop 1
	v_add_f32_dpp v0, v0, v0 quad_perm:[1,0,3,2] row_mask:0xf bank_mask:0xf
	s_nop 1
	v_add_f32_dpp v0, v0, v0 quad_perm:[2,3,0,1] row_mask:0xf bank_mask:0xf
	s_nop 1
	v_add_f32_dpp v0, v0, v0 row_half_mirror row_mask:0xf bank_mask:0xf
	s_nop 1
	v_add_f32_dpp v0, v0, v0 row_mirror row_mask:0xf bank_mask:0xf
	v_fmamk_f32 v0, v0, 0x3c000000, v232
	v_rsq_f32_e32 v0, v0
	s_waitcnt vmcnt(3)
	v_lshlrev_b32_e32 v246, 16, v212
	v_and_b32_e32 v247, 0xffff0000, v212
	v_lshlrev_b32_e32 v248, 16, v213
	v_and_b32_e32 v249, 0xffff0000, v213
	v_lshlrev_b32_e32 v250, 16, v214
	v_and_b32_e32 v251, 0xffff0000, v214
	v_lshlrev_b32_e32 v252, 16, v215
	v_and_b32_e32 v253, 0xffff0000, v215
	v_mul_f32_e32 v10, 0xbfb8aa3b, v246
	v_mul_f32_e32 v11, 0xbfb8aa3b, v247
	v_mul_f32_e32 v12, 0xbfb8aa3b, v248
	v_mul_f32_e32 v13, 0xbfb8aa3b, v249
	v_mul_f32_e32 v14, 0xbfb8aa3b, v250
	v_mul_f32_e32 v15, 0xbfb8aa3b, v251
	v_mul_f32_e32 v228, 0xbfb8aa3b, v252
	v_mul_f32_e32 v229, 0xbfb8aa3b, v253
	v_exp_f32_e32 v10, v10
	v_exp_f32_e32 v11, v11
	v_exp_f32_e32 v12, v12
	v_exp_f32_e32 v13, v13
	v_exp_f32_e32 v14, v14
	v_exp_f32_e32 v15, v15
	v_exp_f32_e32 v228, v228
	v_exp_f32_e32 v229, v229
	v_add_f32_e32 v10, 1.0, v10
	v_add_f32_e32 v11, 1.0, v11
	v_add_f32_e32 v12, 1.0, v12
	v_add_f32_e32 v13, 1.0, v13
	v_add_f32_e32 v14, 1.0, v14
	v_add_f32_e32 v15, 1.0, v15
	v_add_f32_e32 v228, 1.0, v228
	v_add_f32_e32 v229, 1.0, v229
	v_rcp_f32_e32 v10, v10
	v_rcp_f32_e32 v11, v11
	v_rcp_f32_e32 v12, v12
	v_rcp_f32_e32 v13, v13
	v_rcp_f32_e32 v14, v14
	v_rcp_f32_e32 v15, v15
	v_rcp_f32_e32 v228, v228
	v_rcp_f32_e32 v229, v229
	v_pk_mul_f32 v[2:3], v[2:3], v[0:1] op_sel_hi:[1,0]
	v_pk_mul_f32 v[4:5], v[4:5], v[0:1] op_sel_hi:[1,0]
	v_pk_mul_f32 v[6:7], v[6:7], v[0:1] op_sel_hi:[1,0]
	v_pk_mul_f32 v[8:9], v[8:9], v[0:1] op_sel_hi:[1,0]
	v_pk_mul_f32 v[2:3], v[238:239], v[2:3]
	v_pk_mul_f32 v[4:5], v[240:241], v[4:5]
	v_pk_mul_f32 v[6:7], v[242:243], v[6:7]
	v_pk_mul_f32 v[8:9], v[244:245], v[8:9]
	v_pk_mul_f32 v[246:247], v[10:11], v[246:247]
	v_pk_mul_f32 v[248:249], v[12:13], v[248:249]
	v_pk_mul_f32 v[250:251], v[14:15], v[250:251]
	v_pk_mul_f32 v[252:253], v[228:229], v[252:253]
	v_pk_mul_f32 v[2:3], v[246:247], v[2:3]
	v_pk_mul_f32 v[4:5], v[248:249], v[4:5]
	v_pk_mul_f32 v[6:7], v[250:251], v[6:7]
	v_pk_mul_f32 v[8:9], v[252:253], v[8:9]
	v_cvt_pk_bf16_f32 v10, v2, v3
	v_cvt_pk_bf16_f32 v11, v4, v5
	v_cvt_pk_bf16_f32 v12, v6, v7
	v_cvt_pk_bf16_f32 v13, v8, v9
	global_store_dwordx4 v227, v[10:13], s[70:71]
	v_add_u32_e32 v227, 0x2000, v227
	ds_read_b128 v[2:5], v226 offset:4224
	ds_read_b128 v[6:9], v226 offset:4240
	s_waitcnt lgkmcnt(0)
	v_mul_f32_e32 v0, v2, v2
	v_fmac_f32_e32 v0, v3, v3
	v_fmac_f32_e32 v0, v4, v4
	v_fmac_f32_e32 v0, v5, v5
	v_fmac_f32_e32 v0, v6, v6
	v_fmac_f32_e32 v0, v7, v7
	v_fmac_f32_e32 v0, v8, v8
	v_fmac_f32_e32 v0, v9, v9
	s_nop 1
	v_add_f32_dpp v0, v0, v0 quad_perm:[1,0,3,2] row_mask:0xf bank_mask:0xf
	s_nop 1
	v_add_f32_dpp v0, v0, v0 quad_perm:[2,3,0,1] row_mask:0xf bank_mask:0xf
	s_nop 1
	v_add_f32_dpp v0, v0, v0 row_half_mirror row_mask:0xf bank_mask:0xf
	s_nop 1
	v_add_f32_dpp v0, v0, v0 row_mirror row_mask:0xf bank_mask:0xf
	v_fmamk_f32 v0, v0, 0x3c000000, v232
	v_rsq_f32_e32 v0, v0
	s_waitcnt vmcnt(3)
; __device__ __forceinline__ float sigm(float x) { return __builtin_amdgcn_rcpf(1.0f + __expf(-x)); }
; __device__ __forceinline__ float bflo(unsigned w) { return __uint_as_float(w << 16); }
; __device__ __forceinline__ float bfhi(unsigned w) { return __uint_as_float(w & 0xffff0000u); }
; #define LAS __attribute__((address_space(3)))
; __device__ __forceinline__ unsigned pk2(float lo, float hi) { return pg8::cvt_pk_bf16(lo, hi); }
; __device__ __forceinline__ void ret_out_unit(LAS unsigned char* lds, const bf16* Z, const bf16* RT, const float* subg, bf16* YB, int h, int n, int tid) {
;     ...
;     for (int rr = 0; rr < 16; ++rr) {
;         const int i = wid * 16 + rr;
;         const f32x2 x = *(const LAS f32x2*)(OF + i * 132 + 2 * lane);
;         const float r = rsqrtf(wave_sum(x.x * x.x + x.y * x.y) * (1.f / 128.f) + EPS);
;         const size_t row = (size_t)(n * 128 + i);
;         const unsigned gw = *(const unsigned*)(Z + row * NIN + ZGR + h * 128 + 2 * lane);
;         const float ga = bflo(gw), gb = bfhi(gw);
;         *(unsigned*)(YB + row * 1024 + h * 128 + 2 * lane) = pk2(x.x * r * g2.x * (ga * sigm(ga)), x.y * r * g2.y * (gb * sigm(gb)));
;     }
;     __syncthreads();
	v_lshlrev_b32_e32 v246, 16, v216
	v_and_b32_e32 v247, 0xffff0000, v216
	v_lshlrev_b32_e32 v248, 16, v217
	v_and_b32_e32 v249, 0xffff0000, v217
	v_lshlrev_b32_e32 v250, 16, v218
	v_and_b32_e32 v251, 0xffff0000, v218
	v_lshlrev_b32_e32 v252, 16, v219
	v_and_b32_e32 v253, 0xffff0000, v219
	v_mul_f32_e32 v10, 0xbfb8aa3b, v246
	v_mul_f32_e32 v11, 0xbfb8aa3b, v247
	v_mul_f32_e32 v12, 0xbfb8aa3b, v248
	v_mul_f32_e32 v13, 0xbfb8aa3b, v249
	v_mul_f32_e32 v14, 0xbfb8aa3b, v250
	v_mul_f32_e32 v15, 0xbfb8aa3b, v251
	v_mul_f32_e32 v228, 0xbfb8aa3b, v252
	v_mul_f32_e32 v229, 0xbfb8aa3b, v253
	v_exp_f32_e32 v10, v10
	v_exp_f32_e32 v11, v11
	v_exp_f32_e32 v12, v12
	v_exp_f32_e32 v13, v13
	v_exp_f32_e32 v14, v14
	v_exp_f32_e32 v15, v15
	v_exp_f32_e32 v228, v228
	v_exp_f32_e32 v229, v229
	v_add_f32_e32 v10, 1.0, v10
	v_add_f32_e32 v11, 1.0, v11
	v_add_f32_e32 v12, 1.0, v12
	v_add_f32_e32 v13, 1.0, v13
	v_add_f32_e32 v14, 1.0, v14
	v_add_f32_e32 v15, 1.0, v15
	v_add_f32_e32 v228, 1.0, v228
	v_add_f32_e32 v229, 1.0, v229
	v_rcp_f32_e32 v10, v10
	v_rcp_f32_e32 v11, v11
	v_rcp_f32_e32 v12, v12
	v_rcp_f32_e32 v13, v13
	v_rcp_f32_e32 v14, v14
	v_rcp_f32_e32 v15, v15
	v_rcp_f32_e32 v228, v228
	v_rcp_f32_e32 v229, v229
	v_pk_mul_f32 v[2:3], v[2:3], v[0:1] op_sel_hi:[1,0]
	v_pk_mul_f32 v[4:5], v[4:5], v[0:1] op_sel_hi:[1,0]
	v_pk_mul_f32 v[6:7], v[6:7], v[0:1] op_sel_hi:[1,0]
	v_pk_mul_f32 v[8:9], v[8:9], v[0:1] op_sel_hi:[1,0]
	v_pk_mul_f32 v[2:3], v[238:239], v[2:3]
	v_pk_mul_f32 v[4:5], v[240:241], v[4:5]
	v_pk_mul_f32 v[6:7], v[242:243], v[6:7]
	v_pk_mul_f32 v[8:9], v[244:245], v[8:9]
	v_pk_mul_f32 v[246:247], v[10:11], v[246:247]
	v_pk_mul_f32 v[248:249], v[12:13], v[248:249]
	v_pk_mul_f32 v[250:251], v[14:15], v[250:251]
	v_pk_mul_f32 v[252:253], v[228:229], v[252:253]
	v_pk_mul_f32 v[2:3], v[246:247], v[2:3]
	v_pk_mul_f32 v[4:5], v[248:249], v[4:5]
	v_pk_mul_f32 v[6:7], v[250:251], v[6:7]
	v_pk_mul_f32 v[8:9], v[252:253], v[8:9]
	v_cvt_pk_bf16_f32 v10, v2, v3
	v_cvt_pk_bf16_f32 v11, v4, v5
	v_cvt_pk_bf16_f32 v12, v6, v7
	v_cvt_pk_bf16_f32 v13, v8, v9
	global_store_dwordx4 v227, v[10:13], s[70:71]
	v_add_u32_e32 v227, 0x2000, v227
	ds_read_b128 v[2:5], v226 offset:6336
	ds_read_b128 v[6:9], v226 offset:6352
	s_waitcnt lgkmcnt(0)
	v_mul_f32_e32 v0, v2, v2
	v_fmac_f32_e32 v0, v3, v3
	v_fmac_f32_e32 v0, v4, v4
	v_fmac_f32_e32 v0, v5, v5
	v_fmac_f32_e32 v0, v6, v6
	v_fmac_f32_e32 v0, v7, v7
	v_fmac_f32_e32 v0, v8, v8
	v_fmac_f32_e32 v0, v9, v9
	s_nop 1
	v_add_f32_dpp v0, v0, v0 quad_perm:[1,0,3,2] row_mask:0xf bank_mask:0xf
	s_nop 1
	v_add_f32_dpp v0, v0, v0 quad_perm:[2,3,0,1] row_mask:0xf bank_mask:0xf
	s_nop 1
	v_add_f32_dpp v0, v0, v0 row_half_mirror row_mask:0xf bank_mask:0xf
	s_nop 1
	v_add_f32_dpp v0, v0, v0 row_mirror row_mask:0xf bank_mask:0xf
	v_fmamk_f32 v0, v0, 0x3c000000, v232
	v_rsq_f32_e32 v0, v0
	s_waitcnt vmcnt(3)
	v_lshlrev_b32_e32 v246, 16, v220
	v_and_b32_e32 v247, 0xffff0000, v220
	v_lshlrev_b32_e32 v248, 16, v221
	v_and_b32_e32 v249, 0xffff0000, v221
	v_lshlrev_b32_e32 v250, 16, v222
	v_and_b32_e32 v251, 0xffff0000, v222
	v_lshlrev_b32_e32 v252, 16, v223
	v_and_b32_e32 v253, 0xffff0000, v223
	v_mul_f32_e32 v10, 0xbfb8aa3b, v246
	v_mul_f32_e32 v11, 0xbfb8aa3b, v247
	v_mul_f32_e32 v12, 0xbfb8aa3b, v248
	v_mul_f32_e32 v13, 0xbfb8aa3b, v249
	v_mul_f32_e32 v14, 0xbfb8aa3b, v250
	v_mul_f32_e32 v15, 0xbfb8aa3b, v251
	v_mul_f32_e32 v228, 0xbfb8aa3b, v252
	v_mul_f32_e32 v229, 0xbfb8aa3b, v253
	v_exp_f32_e32 v10, v10
	v_exp_f32_e32 v11, v11
	v_exp_f32_e32 v12, v12
	v_exp_f32_e32 v13, v13
	v_exp_f32_e32 v14, v14
	v_exp_f32_e32 v15, v15
	v_exp_f32_e32 v228, v228
	v_exp_f32_e32 v229, v229
	v_add_f32_e32 v10, 1.0, v10
	v_add_f32_e32 v11, 1.0, v11
	v_add_f32_e32 v12, 1.0, v12
	v_add_f32_e32 v13, 1.0, v13
	v_add_f32_e32 v14, 1.0, v14
	v_add_f32_e32 v15, 1.0, v15
	v_add_f32_e32 v228, 1.0, v228
	v_add_f32_e32 v229, 1.0, v229
	v_rcp_f32_e32 v10, v10
	v_rcp_f32_e32 v11, v11
	v_rcp_f32_e32 v12, v12
	v_rcp_f32_e32 v13, v13
	v_rcp_f32_e32 v14, v14
	v_rcp_f32_e32 v15, v15
	v_rcp_f32_e32 v228, v228
	v_rcp_f32_e32 v229, v229
	v_pk_mul_f32 v[2:3], v[2:3], v[0:1] op_sel_hi:[1,0]
	v_pk_mul_f32 v[4:5], v[4:5], v[0:1] op_sel_hi:[1,0]
	v_pk_mul_f32 v[6:7], v[6:7], v[0:1] op_sel_hi:[1,0]
	v_pk_mul_f32 v[8:9], v[8:9], v[0:1] op_sel_hi:[1,0]
	v_pk_mul_f32 v[2:3], v[238:239], v[2:3]
	v_pk_mul_f32 v[4:5], v[240:241], v[4:5]
	v_pk_mul_f32 v[6:7], v[242:243], v[6:7]
	v_pk_mul_f32 v[8:9], v[244:245], v[8:9]
	v_pk_mul_f32 v[246:247], v[10:11], v[246:247]
	v_pk_mul_f32 v[248:249], v[12:13], v[248:249]
	v_pk_mul_f32 v[250:251], v[14:15], v[250:251]
	v_pk_mul_f32 v[252:253], v[228:229], v[252:253]
	v_pk_mul_f32 v[2:3], v[246:247], v[2:3]
	v_pk_mul_f32 v[4:5], v[248:249], v[4:5]
	v_pk_mul_f32 v[6:7], v[250:251], v[6:7]
	v_pk_mul_f32 v[8:9], v[252:253], v[8:9]
	v_cvt_pk_bf16_f32 v10, v2, v3
	v_cvt_pk_bf16_f32 v11, v4, v5
	v_cvt_pk_bf16_f32 v12, v6, v7
	v_cvt_pk_bf16_f32 v13, v8, v9
	global_store_dwordx4 v227, v[10:13], s[70:71]
	s_add_i32 s0, s0, s2
	s_add_i32 s3, s3, s2
	s_cmpk_gt_i32 s0, 0x3ff
	s_barrier
	s_cbranch_scc0 .LBB0_14
